# baseline (speedup 1.0000x reference)
; __device__ __forceinline__ void stg16f(void* p, float a, float b, float c, float d) { typedef float f32x4_ __attribute__((ext_vector_type(4))); const f32x4_ v = {a, b, c, d}; *(__attribute__((address_space(1))) f32x4_*)(p) = v; }
; __device__ __forceinline__ float4 ldg16f(const void* p) { typedef float f32x4_ __attribute__((ext_vector_type(4))); const f32x4_ v = *(const __attribute__((address_space(1))) f32x4_*)(p); return make_float4(v.x, v.y, v.z, v.w); }
; #define EPI_LOOP(...) _Pragma("unroll") for (int ai = 0; ai < 2; ++ai) _Pragma("unroll") for (int bj = 0; bj < 2; ++bj) \
;     _Pragma("unroll") for (int m = 0; m < 4; ++m) _Pragma("unroll") for (int n = 0; n < 2; ++n) { \
;       const int o = toff + (ai * HALF + m * 16) * ld + bj * HALF + n * 16; const f32x4 v = acc[ai][bj][m][n]; __VA_ARGS__ }
; template <class EPIF>
; __device__ __forceinline__ void gemm_stream(const u16* __restrict__ A, const u16* __restrict__ Bt, const int K, const int nM,
;                                             const int nN, const int loc, const int G, EPIF epif, u16* shm, const int wv) {
;     ...
;         float* d = (float*)ep.dst + (long)brow * ld + ccol;
;         const float* r = ep.res + (long)brow * ld + ccol;
;         EPI_LOOP({ const float4 rv = ldg16f(r + o); stg16f(d + o, rv.x + v[0], rv.y + v[1], rv.z + v[2], rv.w + v[3]); })
.LBB0_293:
	s_lshl_b64 s[8:9], s[24:25], 2
	s_lshl_b64 s[10:11], s[22:23], 2
	s_waitcnt vmcnt(0) lgkmcnt(0)
	v_lshl_add_u64 v[152:153], v[134:135], 0, s[8:9]
	v_lshl_add_u64 v[150:151], v[146:147], 0, s[8:9]
	v_lshl_add_u64 v[152:153], v[152:153], 0, s[10:11]
	v_lshl_add_u64 v[150:151], v[150:151], 0, s[10:11]
	s_lshl_b32 s8, s83, 4
	s_lshl_b32 s9, s83, 7
	s_mov_b32 s10, 0
	v_add_u32_e32 v182, s10, v148
	v_ashrrev_i32_e32 v183, 31, v182
	v_lshlrev_b64 v[182:183], 2, v[182:183]
	v_lshl_add_u64 v[174:175], v[152:153], 0, v[182:183]
	global_load_dwordx4 v[186:189], v[174:175], off
	global_load_dwordx4 v[190:193], v[174:175], off offset:64
	global_load_dwordx4 v[194:197], v[174:175], off offset:512
	global_load_dwordx4 v[198:201], v[174:175], off offset:576
	s_mul_i32 s10, s8, 1
	v_add_u32_e32 v182, s10, v148
	v_ashrrev_i32_e32 v183, 31, v182
	v_lshlrev_b64 v[182:183], 2, v[182:183]
	v_lshl_add_u64 v[174:175], v[152:153], 0, v[182:183]
	global_load_dwordx4 v[202:205], v[174:175], off
	global_load_dwordx4 v[206:209], v[174:175], off offset:64
	global_load_dwordx4 v[216:219], v[174:175], off offset:512
	global_load_dwordx4 v[220:223], v[174:175], off offset:576
	s_mul_i32 s10, s8, 2
	v_add_u32_e32 v182, s10, v148
	v_ashrrev_i32_e32 v183, 31, v182
	v_lshlrev_b64 v[182:183], 2, v[182:183]
	v_lshl_add_u64 v[174:175], v[152:153], 0, v[182:183]
	global_load_dwordx4 v[224:227], v[174:175], off
	global_load_dwordx4 v[232:235], v[174:175], off offset:64
	global_load_dwordx4 v[240:243], v[174:175], off offset:512
	global_load_dwordx4 v[178:181], v[174:175], off offset:576
	s_mov_b32 s10, 0
	v_add_u32_e32 v182, s10, v148
	v_ashrrev_i32_e32 v183, 31, v182
	v_lshlrev_b64 v[182:183], 2, v[182:183]
	v_lshl_add_u64 v[176:177], v[150:151], 0, v[182:183]
	s_mul_i32 s10, s8, 3
	v_add_u32_e32 v182, s10, v148
	v_ashrrev_i32_e32 v183, 31, v182
	v_lshlrev_b64 v[182:183], 2, v[182:183]
	v_lshl_add_u64 v[174:175], v[152:153], 0, v[182:183]
	s_waitcnt vmcnt(11)
	v_pk_add_f32 v[186:187], v[124:125], v[186:187]
	v_pk_add_f32 v[188:189], v[126:127], v[188:189]
	global_store_dwordx4 v[176:177], v[186:189], off
	global_load_dwordx4 v[186:189], v[174:175], off
	s_waitcnt vmcnt(12)
	v_pk_add_f32 v[190:191], v[120:121], v[190:191]
	v_pk_add_f32 v[192:193], v[122:123], v[192:193]
	global_store_dwordx4 v[176:177], v[190:193], off offset:64
	global_load_dwordx4 v[190:193], v[174:175], off offset:64
	s_waitcnt vmcnt(13)
	v_pk_add_f32 v[194:195], v[108:109], v[194:195]
	v_pk_add_f32 v[196:197], v[110:111], v[196:197]
	global_store_dwordx4 v[176:177], v[194:197], off offset:512
	global_load_dwordx4 v[194:197], v[174:175], off offset:512
	s_waitcnt vmcnt(14)
	v_pk_add_f32 v[198:199], v[104:105], v[198:199]
	v_pk_add_f32 v[200:201], v[106:107], v[200:201]
	global_store_dwordx4 v[176:177], v[198:201], off offset:576
	global_load_dwordx4 v[198:201], v[174:175], off offset:576
	s_mul_i32 s10, s8, 1
	v_add_u32_e32 v182, s10, v148
	v_ashrrev_i32_e32 v183, 31, v182
	v_lshlrev_b64 v[182:183], 2, v[182:183]
	v_lshl_add_u64 v[176:177], v[150:151], 0, v[182:183]
	s_mov_b32 s10, 0
	s_add_i32 s10, s10, s9
	v_add_u32_e32 v182, s10, v148
	v_ashrrev_i32_e32 v183, 31, v182
	v_lshlrev_b64 v[182:183], 2, v[182:183]
	v_lshl_add_u64 v[174:175], v[152:153], 0, v[182:183]
	s_waitcnt vmcnt(15)
	v_pk_add_f32 v[202:203], v[116:117], v[202:203]
	v_pk_add_f32 v[204:205], v[118:119], v[204:205]
	global_store_dwordx4 v[176:177], v[202:205], off
	global_load_dwordx4 v[202:205], v[174:175], off
	s_waitcnt vmcnt(16)
	v_pk_add_f32 v[206:207], v[112:113], v[206:207]
	v_pk_add_f32 v[208:209], v[114:115], v[208:209]
	global_store_dwordx4 v[176:177], v[206:209], off offset:64
	global_load_dwordx4 v[206:209], v[174:175], off offset:64
	s_waitcnt vmcnt(17)
	v_pk_add_f32 v[216:217], v[92:93], v[216:217]
	v_pk_add_f32 v[218:219], v[94:95], v[218:219]
	global_store_dwordx4 v[176:177], v[216:219], off offset:512
	global_load_dwordx4 v[216:219], v[174:175], off offset:512
	s_waitcnt vmcnt(18)
	v_pk_add_f32 v[220:221], v[88:89], v[220:221]
	v_pk_add_f32 v[222:223], v[90:91], v[222:223]
	global_store_dwordx4 v[176:177], v[220:223], off offset:576
	global_load_dwordx4 v[220:223], v[174:175], off offset:576
	s_mul_i32 s10, s8, 2
	v_add_u32_e32 v182, s10, v148
	v_ashrrev_i32_e32 v183, 31, v182
	v_lshlrev_b64 v[182:183], 2, v[182:183]
	v_lshl_add_u64 v[176:177], v[150:151], 0, v[182:183]
	s_mul_i32 s10, s8, 1
	s_add_i32 s10, s10, s9
	v_add_u32_e32 v182, s10, v148
	v_ashrrev_i32_e32 v183, 31, v182
	v_lshlrev_b64 v[182:183], 2, v[182:183]
	v_lshl_add_u64 v[174:175], v[152:153], 0, v[182:183]
	s_waitcnt vmcnt(19)
	v_pk_add_f32 v[224:225], v[100:101], v[224:225]
	v_pk_add_f32 v[226:227], v[102:103], v[226:227]
	global_store_dwordx4 v[176:177], v[224:227], off
	global_load_dwordx4 v[224:227], v[174:175], off
	s_waitcnt vmcnt(20)
	v_pk_add_f32 v[232:233], v[96:97], v[232:233]
	v_pk_add_f32 v[234:235], v[98:99], v[234:235]
	global_store_dwordx4 v[176:177], v[232:235], off offset:64
	global_load_dwordx4 v[232:235], v[174:175], off offset:64
	s_waitcnt vmcnt(21)
	v_pk_add_f32 v[240:241], v[72:73], v[240:241]
	v_pk_add_f32 v[242:243], v[74:75], v[242:243]
	global_store_dwordx4 v[176:177], v[240:243], off offset:512
	global_load_dwordx4 v[240:243], v[174:175], off offset:512
	s_waitcnt vmcnt(22)
; __device__ __forceinline__ void stg16f(void* p, float a, float b, float c, float d) { typedef float f32x4_ __attribute__((ext_vector_type(4))); const f32x4_ v = {a, b, c, d}; *(__attribute__((address_space(1))) f32x4_*)(p) = v; }
; __device__ __forceinline__ float4 ldg16f(const void* p) { typedef float f32x4_ __attribute__((ext_vector_type(4))); const f32x4_ v = *(const __attribute__((address_space(1))) f32x4_*)(p); return make_float4(v.x, v.y, v.z, v.w); }
; #define EPI_LOOP(...) _Pragma("unroll") for (int ai = 0; ai < 2; ++ai) _Pragma("unroll") for (int bj = 0; bj < 2; ++bj) \
;     _Pragma("unroll") for (int m = 0; m < 4; ++m) _Pragma("unroll") for (int n = 0; n < 2; ++n) { \
;       const int o = toff + (ai * HALF + m * 16) * ld + bj * HALF + n * 16; const f32x4 v = acc[ai][bj][m][n]; __VA_ARGS__ }
; template <class EPIF>
; __device__ __forceinline__ void gemm_stream(const u16* __restrict__ A, const u16* __restrict__ Bt, const int K, const int nM,
;                                             const int nN, const int loc, const int G, EPIF epif, u16* shm, const int wv) {
;     ...
;         float* d = (float*)ep.dst + (long)brow * ld + ccol;
;         const float* r = ep.res + (long)brow * ld + ccol;
;         EPI_LOOP({ const float4 rv = ldg16f(r + o); stg16f(d + o, rv.x + v[0], rv.y + v[1], rv.z + v[2], rv.w + v[3]); })
	v_pk_add_f32 v[178:179], v[64:65], v[178:179]
	v_pk_add_f32 v[180:181], v[66:67], v[180:181]
	global_store_dwordx4 v[176:177], v[178:181], off offset:576
	global_load_dwordx4 v[178:181], v[174:175], off offset:576
	s_mul_i32 s10, s8, 3
	v_add_u32_e32 v182, s10, v148
	v_ashrrev_i32_e32 v183, 31, v182
	v_lshlrev_b64 v[182:183], 2, v[182:183]
	v_lshl_add_u64 v[176:177], v[150:151], 0, v[182:183]
	s_mul_i32 s10, s8, 2
	s_add_i32 s10, s10, s9
	v_add_u32_e32 v182, s10, v148
	v_ashrrev_i32_e32 v183, 31, v182
	v_lshlrev_b64 v[182:183], 2, v[182:183]
	v_lshl_add_u64 v[174:175], v[152:153], 0, v[182:183]
	s_waitcnt vmcnt(22)
	v_pk_add_f32 v[186:187], v[84:85], v[186:187]
	v_pk_add_f32 v[188:189], v[86:87], v[188:189]
	global_store_dwordx4 v[176:177], v[186:189], off
	global_load_dwordx4 v[186:189], v[174:175], off
	s_waitcnt vmcnt(22)
	v_pk_add_f32 v[190:191], v[80:81], v[190:191]
	v_pk_add_f32 v[192:193], v[82:83], v[192:193]
	global_store_dwordx4 v[176:177], v[190:193], off offset:64
	global_load_dwordx4 v[190:193], v[174:175], off offset:64
	s_waitcnt vmcnt(22)
	v_pk_add_f32 v[194:195], v[56:57], v[194:195]
	v_pk_add_f32 v[196:197], v[58:59], v[196:197]
	global_store_dwordx4 v[176:177], v[194:197], off offset:512
	global_load_dwordx4 v[194:197], v[174:175], off offset:512
	s_waitcnt vmcnt(22)
	v_pk_add_f32 v[198:199], v[48:49], v[198:199]
	v_pk_add_f32 v[200:201], v[50:51], v[200:201]
	global_store_dwordx4 v[176:177], v[198:201], off offset:576
	global_load_dwordx4 v[198:201], v[174:175], off offset:576
	s_mov_b32 s10, 0
	s_add_i32 s10, s10, s9
	v_add_u32_e32 v182, s10, v148
	v_ashrrev_i32_e32 v183, 31, v182
	v_lshlrev_b64 v[182:183], 2, v[182:183]
	v_lshl_add_u64 v[176:177], v[150:151], 0, v[182:183]
	s_mul_i32 s10, s8, 3
	s_add_i32 s10, s10, s9
	v_add_u32_e32 v182, s10, v148
	v_ashrrev_i32_e32 v183, 31, v182
	v_lshlrev_b64 v[182:183], 2, v[182:183]
	v_lshl_add_u64 v[174:175], v[152:153], 0, v[182:183]
	s_waitcnt vmcnt(22)
	v_pk_add_f32 v[202:203], v[76:77], v[202:203]
	v_pk_add_f32 v[204:205], v[78:79], v[204:205]
	global_store_dwordx4 v[176:177], v[202:205], off
	global_load_dwordx4 v[202:205], v[174:175], off
	s_waitcnt vmcnt(22)
	v_pk_add_f32 v[206:207], v[68:69], v[206:207]
	v_pk_add_f32 v[208:209], v[70:71], v[208:209]
	global_store_dwordx4 v[176:177], v[206:209], off offset:64
	global_load_dwordx4 v[206:209], v[174:175], off offset:64
	s_waitcnt vmcnt(22)
	v_pk_add_f32 v[216:217], v[36:37], v[216:217]
	v_pk_add_f32 v[218:219], v[38:39], v[218:219]
	global_store_dwordx4 v[176:177], v[216:219], off offset:512
	global_load_dwordx4 v[216:219], v[174:175], off offset:512
	s_waitcnt vmcnt(22)
	v_pk_add_f32 v[220:221], v[32:33], v[220:221]
	v_pk_add_f32 v[222:223], v[34:35], v[222:223]
	global_store_dwordx4 v[176:177], v[220:223], off offset:576
	global_load_dwordx4 v[220:223], v[174:175], off offset:576
	s_mul_i32 s10, s8, 1
	s_add_i32 s10, s10, s9
	v_add_u32_e32 v182, s10, v148
	v_ashrrev_i32_e32 v183, 31, v182
	v_lshlrev_b64 v[182:183], 2, v[182:183]
	v_lshl_add_u64 v[176:177], v[150:151], 0, v[182:183]
	s_waitcnt vmcnt(22)
	v_pk_add_f32 v[224:225], v[60:61], v[224:225]
	v_pk_add_f32 v[226:227], v[62:63], v[226:227]
	global_store_dwordx4 v[176:177], v[224:227], off
	s_waitcnt vmcnt(21)
	v_pk_add_f32 v[232:233], v[52:53], v[232:233]
	v_pk_add_f32 v[234:235], v[54:55], v[234:235]
	global_store_dwordx4 v[176:177], v[232:235], off offset:64
	s_waitcnt vmcnt(20)
	v_pk_add_f32 v[240:241], v[20:21], v[240:241]
	v_pk_add_f32 v[242:243], v[22:23], v[242:243]
	global_store_dwordx4 v[176:177], v[240:243], off offset:512
	s_waitcnt vmcnt(19)
	v_pk_add_f32 v[178:179], v[16:17], v[178:179]
	v_pk_add_f32 v[180:181], v[18:19], v[180:181]
	global_store_dwordx4 v[176:177], v[178:181], off offset:576
	s_mul_i32 s10, s8, 2
	s_add_i32 s10, s10, s9
	v_add_u32_e32 v182, s10, v148
	v_ashrrev_i32_e32 v183, 31, v182
	v_lshlrev_b64 v[182:183], 2, v[182:183]
	v_lshl_add_u64 v[176:177], v[150:151], 0, v[182:183]
	s_waitcnt vmcnt(18)
	v_pk_add_f32 v[186:187], v[44:45], v[186:187]
	v_pk_add_f32 v[188:189], v[46:47], v[188:189]
	global_store_dwordx4 v[176:177], v[186:189], off
	s_waitcnt vmcnt(17)
	v_pk_add_f32 v[190:191], v[40:41], v[190:191]
	v_pk_add_f32 v[192:193], v[42:43], v[192:193]
	global_store_dwordx4 v[176:177], v[190:193], off offset:64
	s_waitcnt vmcnt(16)
	v_pk_add_f32 v[194:195], v[12:13], v[194:195]
	v_pk_add_f32 v[196:197], v[14:15], v[196:197]
	global_store_dwordx4 v[176:177], v[194:197], off offset:512
	s_waitcnt vmcnt(15)
	v_pk_add_f32 v[198:199], v[8:9], v[198:199]
	v_pk_add_f32 v[200:201], v[10:11], v[200:201]
	global_store_dwordx4 v[176:177], v[198:201], off offset:576
	s_mul_i32 s10, s8, 3
	s_add_i32 s10, s10, s9
	v_add_u32_e32 v182, s10, v148
	v_ashrrev_i32_e32 v183, 31, v182
	v_lshlrev_b64 v[182:183], 2, v[182:183]
	v_lshl_add_u64 v[176:177], v[150:151], 0, v[182:183]
	s_waitcnt vmcnt(14)
	v_pk_add_f32 v[202:203], v[28:29], v[202:203]
	v_pk_add_f32 v[204:205], v[30:31], v[204:205]
	global_store_dwordx4 v[176:177], v[202:205], off
	s_waitcnt vmcnt(13)
	v_pk_add_f32 v[206:207], v[24:25], v[206:207]
	v_pk_add_f32 v[208:209], v[26:27], v[208:209]
	global_store_dwordx4 v[176:177], v[206:209], off offset:64
	s_waitcnt vmcnt(12)
	v_pk_add_f32 v[216:217], v[4:5], v[216:217]
	v_pk_add_f32 v[218:219], v[6:7], v[218:219]
	global_store_dwordx4 v[176:177], v[216:219], off offset:512
	s_waitcnt vmcnt(11)
	v_pk_add_f32 v[220:221], v[0:1], v[220:221]
	v_pk_add_f32 v[222:223], v[2:3], v[222:223]
	global_store_dwordx4 v[176:177], v[220:223], off offset:576
	s_cbranch_execnz .LBB0_185
